# attention PH0 item order: odd rounds take item j^16 of the round's head so every workgroup alternates dilation-4 and dilation-16 items (balanced bytes, XCD stays on one head)
# speedup vs baseline: 1.0058x; 1.0058x over previous
.LBB0_718:
	v_add_u32_e32 v2, s1, v107
	v_lshl_add_u32 v2, v2, s0, v50
	global_load_dwordx4 v[22:25], v2, s[18:19]
	v_add_u32_e32 v2, 0xa000, v51
	v_lshl_add_u32 v2, v2, s0, v50
	global_load_dwordx4 v[26:29], v2, s[18:19]
	v_add_u32_e32 v2, 0xc000, v51
	v_lshl_add_u32 v2, v2, s0, v50
	global_load_dwordx4 v[30:33], v2, s[18:19]
	v_add_u32_e32 v2, 0xe000, v51
	v_lshl_add_u32 v2, v2, s0, v50
	global_load_dwordx4 v[34:37], v2, s[18:19]
	v_add_u32_e32 v2, 0x10000, v51
	v_lshl_add_u32 v2, v2, s0, v50
	global_load_dwordx4 v[38:41], v2, s[18:19]
	v_add_u32_e32 v2, 0x12000, v51
	v_lshl_add_u32 v2, v2, s0, v50
	global_load_dwordx4 v[42:45], v2, s[18:19]
	v_add_u32_e32 v2, 0x14000, v51
	v_lshl_add_u32 v2, v2, s0, v50
	global_load_dwordx4 v[46:49], v2, s[18:19]
	v_add_u32_e32 v2, 0x16000, v51
	v_lshl_add_u32 v2, v2, s0, v50
	global_load_dwordx4 v[50:53], v2, s[18:19]
	s_add_i32 s78, s78, s33
	s_cmpk_lt_i32 s78, 0x400
	s_cselect_b64 s[60:61], -1, 0
	s_cmpk_gt_i32 s78, 0x3ff
	s_cselect_b64 s[74:75], -1, 0
	s_and_b64 vcc, exec, s[74:75]
	s_mov_b32 s82, s30
	s_mov_b32 s81, s20
	s_mov_b32 s80, s31
	s_cbranch_vccnz .LBB0_720
	s_lshr_b32 s99, s78, 3
	s_and_b32 s99, s99, 16
	s_xor_b32 s99, s78, s99
	s_and_b32 s0, s99, 31
	s_bfe_u32 s1, s99, 0x30002
	s_and_b32 s79, s99, 3
	v_sub_co_u32_e64 v4, vcc, s0, 16
	v_mov_b32_e32 v2, s1
	s_and_b64 s[0:1], vcc, exec
	s_cselect_b32 s80, 1, 2
	s_cselect_b32 s79, s79, 0
	s_ashr_i32 s0, s99, 5
	s_add_i32 s1, s0, s89
	s_bfe_u32 s82, s99, 0x20005
	s_and_b32 s0, s0, 12
	v_cndmask_b32_e32 v132, v4, v2, vcc
	s_ashr_i32 s81, s1, 4
	s_or_b32 s82, s0, s82
